# GLA final-pass masked-scores stage hand-rewritten (about 500 to 190 instructions per item)
# baseline (speedup 1.0000x reference)
.LBB0_188:
	v_mov_b32_e32 v148, v204
	v_lshlrev_b32_e32 v128, 16, v52
	v_and_b32_e32 v129, 0xffff0000, v52
	v_lshlrev_b32_e32 v130, 16, v53
	v_and_b32_e32 v131, 0xffff0000, v53
	v_lshl_add_u32 v2, v148, 4, 0
	ds_write_b128 v2, v[128:131]
	v_mad_u64_u32 v[2:3], s[8:9], v148, -12, v[2:3]
	v_ashrrev_i32_e32 v3, 3, v148
	ds_write2st64_b32 v2, v59, v58 offset0:32 offset1:40
	ds_write2st64_b32 v2, v57, v56 offset0:48 offset1:56
	v_and_b32_e32 v2, 0x7f, v148
	v_lshlrev_b32_e32 v3, 1, v3
	v_readfirstlane_b32 s7, v148
	v_mul_u32_u24_e32 v2, 0x90, v2
	v_and_b32_e32 v3, 0xffffffe0, v3
	s_ashr_i32 s6, s7, 6
	v_add3_u32 v2, s92, v2, v3
	ds_write_b128 v2, v[44:47]
	ds_write_b128 v2, v[48:51] offset:16
	v_lshlrev_b32_e32 v2, 2, v148
	s_lshl_b32 s8, s6, 10
	v_and_b32_e32 v149, 0xfc, v2
	s_add_i32 s8, s8, 0
	v_add_u32_e32 v148, 0, v149
	v_mov_b32_e32 v150, s8
	v_lshlrev_b32_e32 v146, 16, v89
	v_lshlrev_b32_e32 v147, 16, v81
	v_lshlrev_b32_e32 v140, 16, v87
	v_lshlrev_b32_e32 v141, 16, v79
	v_lshlrev_b32_e32 v138, 16, v84
	v_lshlrev_b32_e32 v139, 16, v78
	v_lshlrev_b32_e32 v136, 16, v83
	v_lshlrev_b32_e32 v137, 16, v55
	v_lshlrev_b32_e32 v134, 16, v91
	v_lshlrev_b32_e32 v135, 16, v85
	v_lshlrev_b32_e32 v132, 16, v90
	v_lshlrev_b32_e32 v133, 16, v82
	v_lshlrev_b32_e32 v130, 16, v88
	v_lshlrev_b32_e32 v131, 16, v80
	v_lshlrev_b32_e32 v128, 16, v86
	v_lshlrev_b32_e32 v129, 16, v54
	s_waitcnt lgkmcnt(0)
	s_barrier
	ds_read2st64_b32 v[88:89], v148 offset0:32 offset1:33
	ds_read2st64_b32 v[84:85], v148 offset0:48 offset1:49
	ds_read2st64_b32 v[90:91], v148 offset0:34 offset1:35
	ds_read2st64_b32 v[86:87], v148 offset0:50 offset1:51
	ds_read2st64_b32 v[78:79], v148 offset0:36 offset1:37
	ds_read2st64_b32 v[58:59], v148 offset0:52 offset1:53
	ds_read2st64_b32 v[80:81], v148 offset0:38 offset1:39
	ds_read2st64_b32 v[82:83], v148 offset0:54 offset1:55
	ds_read2st64_b32 v[54:55], v148 offset0:40 offset1:41
	ds_read2st64_b32 v[50:51], v148 offset0:56 offset1:57
	ds_read2st64_b32 v[56:57], v148 offset0:42 offset1:43
	ds_read2st64_b32 v[52:53], v148 offset0:58 offset1:59
	ds_read2st64_b32 v[44:45], v148 offset0:44 offset1:45
	ds_read2st64_b32 v[2:3], v148 offset0:60 offset1:61
	ds_read2st64_b32 v[46:47], v148 offset0:46 offset1:47
	ds_read2st64_b32 v[48:49], v148 offset0:62 offset1:63
	s_mov_b32 s8, 0x3d800000
	s_and_b32 s7, s7, 0x3fffffc0
	s_lshl_b32 s7, s7, 2
	s_add_i32 s7, s7, 0
	s_ashr_i32 s28, s27, 6
	s_cmp_gt_i32 s6, 0
	s_cselect_b64 vcc, -1, 0
	s_cmp_lt_i32 s6, 0
	v_and_b32_e32 v124, 63, v126
	v_and_b32_e32 v123, 15, v126
	ds_read_b128 v[222:225], v150
	ds_read_b128 v[226:229], v150 offset:16
	ds_read_b128 v[230:233], v150 offset:32
	ds_read_b128 v[234:237], v150 offset:48
	ds_read_b128 v[238:241], v150 offset:64
	ds_read_b128 v[196:199], v150 offset:80
	ds_read_b128 v[200:203], v150 offset:96
	ds_read_b128 v[176:179], v150 offset:112
	s_waitcnt lgkmcnt(0)
	v_pk_mul_f32 v[180:181], v[222:223], v[88:89]
	v_pk_mul_f32 v[174:175], v[238:239], v[84:85]
	v_pk_mul_f32 v[242:243], v[224:225], v[90:91]
	v_pk_mul_f32 v[172:173], v[240:241], v[86:87]
	v_pk_fma_f32 v[180:181], v[226:227], v[78:79], v[180:181]
	v_pk_fma_f32 v[174:175], v[196:197], v[58:59], v[174:175]
	v_pk_fma_f32 v[242:243], v[228:229], v[80:81], v[242:243]
	v_pk_fma_f32 v[172:173], v[198:199], v[82:83], v[172:173]
	v_pk_fma_f32 v[180:181], v[230:231], v[54:55], v[180:181]
	v_pk_fma_f32 v[174:175], v[200:201], v[50:51], v[174:175]
	v_pk_fma_f32 v[242:243], v[232:233], v[56:57], v[242:243]
	v_pk_fma_f32 v[172:173], v[202:203], v[52:53], v[172:173]
	v_pk_fma_f32 v[180:181], v[234:235], v[44:45], v[180:181]
	v_pk_fma_f32 v[174:175], v[176:177], v[2:3], v[174:175]
	v_pk_fma_f32 v[242:243], v[236:237], v[46:47], v[242:243]
	v_pk_fma_f32 v[172:173], v[178:179], v[48:49], v[172:173]
	ds_read_b128 v[222:225], v150 offset:128
	ds_read_b128 v[226:229], v150 offset:144
	ds_read_b128 v[230:233], v150 offset:160
	ds_read_b128 v[234:237], v150 offset:176
	ds_read_b128 v[238:241], v150 offset:192
	ds_read_b128 v[196:199], v150 offset:208
	ds_read_b128 v[200:203], v150 offset:224
	ds_read_b128 v[176:179], v150 offset:240
	v_pk_add_f32 v[180:181], v[180:181], v[242:243]
	v_pk_add_f32 v[174:175], v[174:175], v[172:173]
	v_add_f32_e32 v180, v180, v181
	v_add_f32_e32 v174, v174, v175
	v_add_f32_e32 v180, v127, v180
	v_add_f32_e32 v174, v125, v174
	v_mul_f32_e64 v181, |v180|, s58
	v_mul_f32_e64 v175, |v174|, s58
	v_exp_f32_e32 v181, v181
	v_exp_f32_e32 v175, v175
	v_min_f32_e32 v180, 0, v180
	v_min_f32_e32 v174, 0, v174
	v_add_f32_e32 v181, 1.0, v181
	v_add_f32_e32 v175, 1.0, v175
	v_log_f32_e32 v181, v181
	v_log_f32_e32 v175, v175
	s_nop 0
	v_fma_f32 v151, v180, s82, -v181
	v_fma_f32 v159, v174, s82, -v175
	s_waitcnt lgkmcnt(0)
	v_pk_mul_f32 v[180:181], v[222:223], v[88:89]
	v_pk_mul_f32 v[174:175], v[238:239], v[84:85]
	v_pk_mul_f32 v[242:243], v[224:225], v[90:91]
	v_pk_mul_f32 v[172:173], v[240:241], v[86:87]
	v_pk_fma_f32 v[180:181], v[226:227], v[78:79], v[180:181]
	v_pk_fma_f32 v[174:175], v[196:197], v[58:59], v[174:175]
	v_pk_fma_f32 v[242:243], v[228:229], v[80:81], v[242:243]
	v_pk_fma_f32 v[172:173], v[198:199], v[82:83], v[172:173]
	v_pk_fma_f32 v[180:181], v[230:231], v[54:55], v[180:181]
	v_pk_fma_f32 v[174:175], v[200:201], v[50:51], v[174:175]
	v_pk_fma_f32 v[242:243], v[232:233], v[56:57], v[242:243]
	v_pk_fma_f32 v[172:173], v[202:203], v[52:53], v[172:173]
	v_pk_fma_f32 v[180:181], v[234:235], v[44:45], v[180:181]
	v_pk_fma_f32 v[174:175], v[176:177], v[2:3], v[174:175]
	v_pk_fma_f32 v[242:243], v[236:237], v[46:47], v[242:243]
	v_pk_fma_f32 v[172:173], v[178:179], v[48:49], v[172:173]
	ds_read_b128 v[222:225], v150 offset:256
	ds_read_b128 v[226:229], v150 offset:272
	ds_read_b128 v[230:233], v150 offset:288
	ds_read_b128 v[234:237], v150 offset:304
	ds_read_b128 v[238:241], v150 offset:320
	ds_read_b128 v[196:199], v150 offset:336
	ds_read_b128 v[200:203], v150 offset:352
	ds_read_b128 v[176:179], v150 offset:368
	v_pk_add_f32 v[180:181], v[180:181], v[242:243]
	v_pk_add_f32 v[174:175], v[174:175], v[172:173]
	v_add_f32_e32 v180, v180, v181
	v_add_f32_e32 v174, v174, v175
	v_add_f32_e32 v180, v127, v180
	v_add_f32_e32 v174, v125, v174
	v_mul_f32_e64 v181, |v180|, s58
	v_mul_f32_e64 v175, |v174|, s58
	v_exp_f32_e32 v181, v181
	v_exp_f32_e32 v175, v175
	v_min_f32_e32 v180, 0, v180
	v_min_f32_e32 v174, 0, v174
	v_add_f32_e32 v181, 1.0, v181
	v_add_f32_e32 v175, 1.0, v175
	v_log_f32_e32 v181, v181
	v_log_f32_e32 v175, v175
	s_nop 0
	v_fma_f32 v152, v180, s82, -v181
	v_fma_f32 v160, v174, s82, -v175
	s_waitcnt lgkmcnt(0)
	v_pk_mul_f32 v[180:181], v[222:223], v[88:89]
	v_pk_mul_f32 v[174:175], v[238:239], v[84:85]
	v_pk_mul_f32 v[242:243], v[224:225], v[90:91]
	v_pk_mul_f32 v[172:173], v[240:241], v[86:87]
	v_pk_fma_f32 v[180:181], v[226:227], v[78:79], v[180:181]
	v_pk_fma_f32 v[174:175], v[196:197], v[58:59], v[174:175]
	v_pk_fma_f32 v[242:243], v[228:229], v[80:81], v[242:243]
	v_pk_fma_f32 v[172:173], v[198:199], v[82:83], v[172:173]
	v_pk_fma_f32 v[180:181], v[230:231], v[54:55], v[180:181]
	v_pk_fma_f32 v[174:175], v[200:201], v[50:51], v[174:175]
	v_pk_fma_f32 v[242:243], v[232:233], v[56:57], v[242:243]
	v_pk_fma_f32 v[172:173], v[202:203], v[52:53], v[172:173]
	v_pk_fma_f32 v[180:181], v[234:235], v[44:45], v[180:181]
	v_pk_fma_f32 v[174:175], v[176:177], v[2:3], v[174:175]
	v_pk_fma_f32 v[242:243], v[236:237], v[46:47], v[242:243]
	v_pk_fma_f32 v[172:173], v[178:179], v[48:49], v[172:173]
	ds_read_b128 v[222:225], v150 offset:384
	ds_read_b128 v[226:229], v150 offset:400
	ds_read_b128 v[230:233], v150 offset:416
	ds_read_b128 v[234:237], v150 offset:432
	ds_read_b128 v[238:241], v150 offset:448
	ds_read_b128 v[196:199], v150 offset:464
	ds_read_b128 v[200:203], v150 offset:480
	ds_read_b128 v[176:179], v150 offset:496
	v_pk_add_f32 v[180:181], v[180:181], v[242:243]
	v_pk_add_f32 v[174:175], v[174:175], v[172:173]
	v_add_f32_e32 v180, v180, v181
	v_add_f32_e32 v174, v174, v175
	v_add_f32_e32 v180, v127, v180
	v_add_f32_e32 v174, v125, v174
	v_mul_f32_e64 v181, |v180|, s58
	v_mul_f32_e64 v175, |v174|, s58
	v_exp_f32_e32 v181, v181
	v_exp_f32_e32 v175, v175
	v_min_f32_e32 v180, 0, v180
	v_min_f32_e32 v174, 0, v174
	v_add_f32_e32 v181, 1.0, v181
	v_add_f32_e32 v175, 1.0, v175
	v_log_f32_e32 v181, v181
	v_log_f32_e32 v175, v175
	s_nop 0
	v_fma_f32 v153, v180, s82, -v181
	v_fma_f32 v161, v174, s82, -v175
	s_waitcnt lgkmcnt(0)
	v_pk_mul_f32 v[180:181], v[222:223], v[88:89]
	v_pk_mul_f32 v[174:175], v[238:239], v[84:85]
	v_pk_mul_f32 v[242:243], v[224:225], v[90:91]
	v_pk_mul_f32 v[172:173], v[240:241], v[86:87]
	v_pk_fma_f32 v[180:181], v[226:227], v[78:79], v[180:181]
	v_pk_fma_f32 v[174:175], v[196:197], v[58:59], v[174:175]
	v_pk_fma_f32 v[242:243], v[228:229], v[80:81], v[242:243]
	v_pk_fma_f32 v[172:173], v[198:199], v[82:83], v[172:173]
	v_pk_fma_f32 v[180:181], v[230:231], v[54:55], v[180:181]
	v_pk_fma_f32 v[174:175], v[200:201], v[50:51], v[174:175]
	v_pk_fma_f32 v[242:243], v[232:233], v[56:57], v[242:243]
	v_pk_fma_f32 v[172:173], v[202:203], v[52:53], v[172:173]
	v_pk_fma_f32 v[180:181], v[234:235], v[44:45], v[180:181]
	v_pk_fma_f32 v[174:175], v[176:177], v[2:3], v[174:175]
	v_pk_fma_f32 v[242:243], v[236:237], v[46:47], v[242:243]
	v_pk_fma_f32 v[172:173], v[178:179], v[48:49], v[172:173]
	ds_read_b128 v[222:225], v150 offset:512
	ds_read_b128 v[226:229], v150 offset:528
	ds_read_b128 v[230:233], v150 offset:544
	ds_read_b128 v[234:237], v150 offset:560
	ds_read_b128 v[238:241], v150 offset:576
	ds_read_b128 v[196:199], v150 offset:592
	ds_read_b128 v[200:203], v150 offset:608
	ds_read_b128 v[176:179], v150 offset:624
	v_pk_add_f32 v[180:181], v[180:181], v[242:243]
	v_pk_add_f32 v[174:175], v[174:175], v[172:173]
	v_add_f32_e32 v180, v180, v181
	v_add_f32_e32 v174, v174, v175
	v_add_f32_e32 v180, v127, v180
	v_add_f32_e32 v174, v125, v174
	v_mul_f32_e64 v181, |v180|, s58
	v_mul_f32_e64 v175, |v174|, s58
	v_exp_f32_e32 v181, v181
	v_exp_f32_e32 v175, v175
	v_min_f32_e32 v180, 0, v180
	v_min_f32_e32 v174, 0, v174
	v_add_f32_e32 v181, 1.0, v181
	v_add_f32_e32 v175, 1.0, v175
	v_log_f32_e32 v181, v181
	v_log_f32_e32 v175, v175
	s_nop 0
	v_fma_f32 v154, v180, s82, -v181
	v_fma_f32 v162, v174, s82, -v175
	s_waitcnt lgkmcnt(0)
	v_pk_mul_f32 v[180:181], v[222:223], v[88:89]
	v_pk_mul_f32 v[174:175], v[238:239], v[84:85]
	v_pk_mul_f32 v[242:243], v[224:225], v[90:91]
	v_pk_mul_f32 v[172:173], v[240:241], v[86:87]
	v_pk_fma_f32 v[180:181], v[226:227], v[78:79], v[180:181]
	v_pk_fma_f32 v[174:175], v[196:197], v[58:59], v[174:175]
	v_pk_fma_f32 v[242:243], v[228:229], v[80:81], v[242:243]
	v_pk_fma_f32 v[172:173], v[198:199], v[82:83], v[172:173]
	v_pk_fma_f32 v[180:181], v[230:231], v[54:55], v[180:181]
	v_pk_fma_f32 v[174:175], v[200:201], v[50:51], v[174:175]
	v_pk_fma_f32 v[242:243], v[232:233], v[56:57], v[242:243]
	v_pk_fma_f32 v[172:173], v[202:203], v[52:53], v[172:173]
	v_pk_fma_f32 v[180:181], v[234:235], v[44:45], v[180:181]
	v_pk_fma_f32 v[174:175], v[176:177], v[2:3], v[174:175]
	v_pk_fma_f32 v[242:243], v[236:237], v[46:47], v[242:243]
	v_pk_fma_f32 v[172:173], v[178:179], v[48:49], v[172:173]
	ds_read_b128 v[222:225], v150 offset:640
	ds_read_b128 v[226:229], v150 offset:656
	ds_read_b128 v[230:233], v150 offset:672
	ds_read_b128 v[234:237], v150 offset:688
	ds_read_b128 v[238:241], v150 offset:704
	ds_read_b128 v[196:199], v150 offset:720
	ds_read_b128 v[200:203], v150 offset:736
	ds_read_b128 v[176:179], v150 offset:752
	v_pk_add_f32 v[180:181], v[180:181], v[242:243]
	v_pk_add_f32 v[174:175], v[174:175], v[172:173]
	v_add_f32_e32 v180, v180, v181
	v_add_f32_e32 v174, v174, v175
	v_add_f32_e32 v180, v127, v180
	v_add_f32_e32 v174, v125, v174
	v_mul_f32_e64 v181, |v180|, s58
	v_mul_f32_e64 v175, |v174|, s58
	v_exp_f32_e32 v181, v181
	v_exp_f32_e32 v175, v175
	v_min_f32_e32 v180, 0, v180
	v_min_f32_e32 v174, 0, v174
	v_add_f32_e32 v181, 1.0, v181
	v_add_f32_e32 v175, 1.0, v175
	v_log_f32_e32 v181, v181
	v_log_f32_e32 v175, v175
	s_nop 0
	v_fma_f32 v155, v180, s82, -v181
	v_fma_f32 v163, v174, s82, -v175
	s_waitcnt lgkmcnt(0)
	v_pk_mul_f32 v[180:181], v[222:223], v[88:89]
	v_pk_mul_f32 v[174:175], v[238:239], v[84:85]
	v_pk_mul_f32 v[242:243], v[224:225], v[90:91]
	v_pk_mul_f32 v[172:173], v[240:241], v[86:87]
	v_pk_fma_f32 v[180:181], v[226:227], v[78:79], v[180:181]
	v_pk_fma_f32 v[174:175], v[196:197], v[58:59], v[174:175]
	v_pk_fma_f32 v[242:243], v[228:229], v[80:81], v[242:243]
	v_pk_fma_f32 v[172:173], v[198:199], v[82:83], v[172:173]
	v_pk_fma_f32 v[180:181], v[230:231], v[54:55], v[180:181]
	v_pk_fma_f32 v[174:175], v[200:201], v[50:51], v[174:175]
	v_pk_fma_f32 v[242:243], v[232:233], v[56:57], v[242:243]
	v_pk_fma_f32 v[172:173], v[202:203], v[52:53], v[172:173]
	v_pk_fma_f32 v[180:181], v[234:235], v[44:45], v[180:181]
	v_pk_fma_f32 v[174:175], v[176:177], v[2:3], v[174:175]
	v_pk_fma_f32 v[242:243], v[236:237], v[46:47], v[242:243]
	v_pk_fma_f32 v[172:173], v[178:179], v[48:49], v[172:173]
	ds_read_b128 v[222:225], v150 offset:768
	ds_read_b128 v[226:229], v150 offset:784
	ds_read_b128 v[230:233], v150 offset:800
	ds_read_b128 v[234:237], v150 offset:816
	ds_read_b128 v[238:241], v150 offset:832
	ds_read_b128 v[196:199], v150 offset:848
	ds_read_b128 v[200:203], v150 offset:864
	ds_read_b128 v[176:179], v150 offset:880
	v_pk_add_f32 v[180:181], v[180:181], v[242:243]
	v_pk_add_f32 v[174:175], v[174:175], v[172:173]
	v_add_f32_e32 v180, v180, v181
	v_add_f32_e32 v174, v174, v175
	v_add_f32_e32 v180, v127, v180
	v_add_f32_e32 v174, v125, v174
	v_mul_f32_e64 v181, |v180|, s58
	v_mul_f32_e64 v175, |v174|, s58
	v_exp_f32_e32 v181, v181
	v_exp_f32_e32 v175, v175
	v_min_f32_e32 v180, 0, v180
	v_min_f32_e32 v174, 0, v174
	v_add_f32_e32 v181, 1.0, v181
	v_add_f32_e32 v175, 1.0, v175
	v_log_f32_e32 v181, v181
	v_log_f32_e32 v175, v175
	s_nop 0
	v_fma_f32 v156, v180, s82, -v181
	v_fma_f32 v164, v174, s82, -v175
	s_waitcnt lgkmcnt(0)
	v_pk_mul_f32 v[180:181], v[222:223], v[88:89]
	v_pk_mul_f32 v[174:175], v[238:239], v[84:85]
	v_pk_mul_f32 v[242:243], v[224:225], v[90:91]
	v_pk_mul_f32 v[172:173], v[240:241], v[86:87]
	v_pk_fma_f32 v[180:181], v[226:227], v[78:79], v[180:181]
	v_pk_fma_f32 v[174:175], v[196:197], v[58:59], v[174:175]
	v_pk_fma_f32 v[242:243], v[228:229], v[80:81], v[242:243]
	v_pk_fma_f32 v[172:173], v[198:199], v[82:83], v[172:173]
	v_pk_fma_f32 v[180:181], v[230:231], v[54:55], v[180:181]
	v_pk_fma_f32 v[174:175], v[200:201], v[50:51], v[174:175]
	v_pk_fma_f32 v[242:243], v[232:233], v[56:57], v[242:243]
	v_pk_fma_f32 v[172:173], v[202:203], v[52:53], v[172:173]
	v_pk_fma_f32 v[180:181], v[234:235], v[44:45], v[180:181]
	v_pk_fma_f32 v[174:175], v[176:177], v[2:3], v[174:175]
	v_pk_fma_f32 v[242:243], v[236:237], v[46:47], v[242:243]
	v_pk_fma_f32 v[172:173], v[178:179], v[48:49], v[172:173]
	ds_read_b128 v[222:225], v150 offset:896
	ds_read_b128 v[226:229], v150 offset:912
	ds_read_b128 v[230:233], v150 offset:928
	ds_read_b128 v[234:237], v150 offset:944
	ds_read_b128 v[238:241], v150 offset:960
	ds_read_b128 v[196:199], v150 offset:976
	ds_read_b128 v[200:203], v150 offset:992
	ds_read_b128 v[176:179], v150 offset:1008
	v_pk_add_f32 v[180:181], v[180:181], v[242:243]
	v_pk_add_f32 v[174:175], v[174:175], v[172:173]
	v_add_f32_e32 v180, v180, v181
	v_add_f32_e32 v174, v174, v175
	v_add_f32_e32 v180, v127, v180
	v_add_f32_e32 v174, v125, v174
	v_mul_f32_e64 v181, |v180|, s58
	v_mul_f32_e64 v175, |v174|, s58
	v_exp_f32_e32 v181, v181
	v_exp_f32_e32 v175, v175
	v_min_f32_e32 v180, 0, v180
	v_min_f32_e32 v174, 0, v174
	v_add_f32_e32 v181, 1.0, v181
	v_add_f32_e32 v175, 1.0, v175
	v_log_f32_e32 v181, v181
	v_log_f32_e32 v175, v175
	s_nop 0
	v_fma_f32 v157, v180, s82, -v181
	v_fma_f32 v165, v174, s82, -v175
	s_waitcnt lgkmcnt(0)
	v_pk_mul_f32 v[180:181], v[222:223], v[88:89]
	v_pk_mul_f32 v[174:175], v[238:239], v[84:85]
	v_pk_mul_f32 v[242:243], v[224:225], v[90:91]
	v_pk_mul_f32 v[172:173], v[240:241], v[86:87]
	v_pk_fma_f32 v[180:181], v[226:227], v[78:79], v[180:181]
	v_pk_fma_f32 v[174:175], v[196:197], v[58:59], v[174:175]
	v_pk_fma_f32 v[242:243], v[228:229], v[80:81], v[242:243]
	v_pk_fma_f32 v[172:173], v[198:199], v[82:83], v[172:173]
	v_pk_fma_f32 v[180:181], v[230:231], v[54:55], v[180:181]
	v_pk_fma_f32 v[174:175], v[200:201], v[50:51], v[174:175]
	v_pk_fma_f32 v[242:243], v[232:233], v[56:57], v[242:243]
	v_pk_fma_f32 v[172:173], v[202:203], v[52:53], v[172:173]
	v_pk_fma_f32 v[180:181], v[234:235], v[44:45], v[180:181]
	v_pk_fma_f32 v[174:175], v[176:177], v[2:3], v[174:175]
	v_pk_fma_f32 v[242:243], v[236:237], v[46:47], v[242:243]
	v_pk_fma_f32 v[172:173], v[178:179], v[48:49], v[172:173]
	v_pk_add_f32 v[180:181], v[180:181], v[242:243]
	v_pk_add_f32 v[174:175], v[174:175], v[172:173]
	v_add_f32_e32 v180, v180, v181
	v_add_f32_e32 v174, v174, v175
	v_add_f32_e32 v180, v127, v180
	v_add_f32_e32 v174, v125, v174
	v_mul_f32_e64 v181, |v180|, s58
	v_mul_f32_e64 v175, |v174|, s58
	v_exp_f32_e32 v181, v181
	v_exp_f32_e32 v175, v175
	v_min_f32_e32 v180, 0, v180
	v_min_f32_e32 v174, 0, v174
	v_add_f32_e32 v181, 1.0, v181
	v_add_f32_e32 v175, 1.0, v175
	v_log_f32_e32 v181, v181
	v_log_f32_e32 v175, v175
	s_nop 0
	v_fma_f32 v158, v180, s82, -v181
	v_fma_f32 v166, v174, s82, -v175
	v_fma_f32 v46, v151, s8, 0
	v_fma_f32 v54, v166, s8, 0
	v_fmamk_f32 v47, v152, 0x3d800000, v46
	v_fmamk_f32 v55, v165, 0x3d800000, v54
	v_fmamk_f32 v48, v153, 0x3d800000, v47
	v_fmamk_f32 v56, v164, 0x3d800000, v55
	v_fmamk_f32 v49, v154, 0x3d800000, v48
	v_fmamk_f32 v57, v163, 0x3d800000, v56
	v_fmamk_f32 v50, v155, 0x3d800000, v49
	v_fmamk_f32 v58, v162, 0x3d800000, v57
	v_fmamk_f32 v51, v156, 0x3d800000, v50
	v_fmamk_f32 v59, v161, 0x3d800000, v58
	v_fmamk_f32 v52, v157, 0x3d800000, v51
	v_fmamk_f32 v78, v160, 0x3d800000, v59
	v_fmamk_f32 v53, v158, 0x3d800000, v52
	v_fmamk_f32 v79, v159, 0x3d800000, v78
	v_add_u32_e32 v2, s7, v149
	ds_write2st64_b32 v2, v53, v79 offset0:64 offset1:72
	s_waitcnt lgkmcnt(0)
	s_barrier
	ds_read2st64_b32 v[2:3], v148 offset0:64 offset1:65
	ds_read2st64_b32 v[44:45], v148 offset0:72 offset1:73
	v_readlane_b32 s8, v245, 52
	s_waitcnt lgkmcnt(0)
	v_add_f32_e32 v2, 0, v2
	v_cndmask_b32_e32 v2, 0, v2, vcc
	s_cselect_b64 vcc, -1, 0
	v_add_f32_e32 v44, 0, v44
	s_cmp_gt_i32 s6, 1
	v_cndmask_b32_e32 v44, 0, v44, vcc
	s_cselect_b64 vcc, -1, 0
	v_add_f32_e32 v3, v2, v3
	s_cmp_lt_i32 s6, 1
	v_cndmask_b32_e32 v80, v2, v3, vcc
	s_cselect_b64 vcc, -1, 0
	v_add_f32_e32 v2, v44, v45
	v_cndmask_b32_e32 v81, 0, v2, vcc
	ds_read2st64_b32 v[2:3], v148 offset0:66 offset1:67
	ds_read2st64_b32 v[44:45], v148 offset0:74 offset1:75
	s_cmp_gt_i32 s6, 2
	s_cselect_b64 vcc, -1, 0
	s_cmp_lt_i32 s6, 2
	s_waitcnt lgkmcnt(0)
	v_add_f32_e32 v2, v80, v2
	v_cndmask_b32_e32 v2, v80, v2, vcc
	s_cselect_b64 vcc, -1, 0
	v_add_f32_e32 v44, v81, v44
	s_cmp_gt_i32 s6, 3
	v_cndmask_b32_e32 v44, 0, v44, vcc
	s_cselect_b64 vcc, -1, 0
	v_add_f32_e32 v3, v2, v3
	s_cmp_lt_i32 s6, 3
	v_cndmask_b32_e32 v80, v2, v3, vcc
	s_cselect_b64 vcc, -1, 0
	v_add_f32_e32 v2, v44, v45
	v_cndmask_b32_e32 v81, 0, v2, vcc
	ds_read2st64_b32 v[2:3], v148 offset0:68 offset1:69
	ds_read2st64_b32 v[44:45], v148 offset0:76 offset1:77
	s_cmp_gt_i32 s6, 4
	s_cselect_b64 vcc, -1, 0
	s_cmp_lt_i32 s6, 4
	s_waitcnt lgkmcnt(0)
	v_add_f32_e32 v2, v80, v2
	v_cndmask_b32_e32 v2, v80, v2, vcc
	s_cselect_b64 vcc, -1, 0
	v_add_f32_e32 v44, v81, v44
	s_cmp_gt_i32 s6, 5
	v_cndmask_b32_e32 v44, 0, v44, vcc
	s_cselect_b64 vcc, -1, 0
	v_add_f32_e32 v3, v2, v3
	s_cmp_lt_i32 s6, 5
	v_cndmask_b32_e32 v80, v2, v3, vcc
	s_cselect_b64 vcc, -1, 0
	v_add_f32_e32 v2, v44, v45
	v_cndmask_b32_e32 v81, 0, v2, vcc
	ds_read2st64_b32 v[2:3], v148 offset0:70 offset1:71
	ds_read2st64_b32 v[44:45], v148 offset0:78 offset1:79
	s_cmp_gt_i32 s6, 6
	s_cselect_b64 vcc, -1, 0
	s_cmp_lt_i32 s6, 6
	s_waitcnt lgkmcnt(0)
	v_add_f32_e32 v2, v80, v2
	v_cndmask_b32_e32 v2, v80, v2, vcc
	s_cselect_b64 vcc, -1, 0
	v_add_f32_e32 v44, v81, v44
	s_cmp_gt_i32 s6, 7
	v_cndmask_b32_e32 v44, 0, v44, vcc
	s_cselect_b64 vcc, -1, 0
	v_add_f32_e32 v3, v2, v3
	s_cmp_lt_i32 s6, 7
	v_cndmask_b32_e32 v2, v2, v3, vcc
	s_cselect_b64 vcc, -1, 0
	v_add_f32_e32 v3, v44, v45
	v_cndmask_b32_e32 v3, 0, v3, vcc
	v_add_f32_e32 v44, v46, v2
	v_add_f32_e32 v45, v79, v3
	v_add_f32_e32 v46, v47, v2
	v_add_f32_e32 v47, v78, v3
	v_add_f32_e32 v48, v48, v2
	v_add_f32_e32 v59, v59, v3
	v_add_f32_e32 v49, v49, v2
	v_add_f32_e32 v58, v58, v3
	v_add_f32_e32 v50, v50, v2
	v_add_f32_e32 v57, v57, v3
	v_add_f32_e32 v51, v51, v2
	v_add_f32_e32 v56, v56, v3
	v_add_f32_e32 v52, v52, v2
	v_add_f32_e32 v55, v55, v3
	v_add_f32_e32 v53, v53, v2
	v_add_f32_e32 v2, v54, v3
	v_exp_f32_e32 v3, v44
	v_exp_f32_e64 v44, -v44
	v_exp_f32_e32 v54, v45
	v_mul_f32_e32 v78, 0x3e000000, v147
	v_mul_f32_e32 v3, v78, v3
	s_mul_i32 s6, s28, 0x240
	v_cvt_pk_bf16_f32 v79, v3, s0
	v_or_b32_e32 v3, s6, v124
	v_mul_f32_e32 v44, v44, v146
	v_lshl_add_u32 v3, v3, 1, 0
	v_cvt_pk_bf16_f32 v44, v44, s0
	ds_write_b16 v3, v44 offset:40960
	v_mul_f32_e32 v44, v78, v54
	v_cvt_pk_bf16_f32 v44, v44, s0
	ds_write_b16 v3, v44 offset:31744
	v_exp_f32_e64 v44, -v45
	v_mul_f32_e32 v54, 0x3e000000, v141
	v_exp_f32_e32 v45, v47
	s_cmpk_lt_u32 s27, 0x100
	v_mul_f32_e32 v44, v44, v146
	v_cvt_pk_bf16_f32 v44, v44, s0
	ds_write_b16 v3, v44 offset:50176
	v_exp_f32_e32 v44, v46
	s_cselect_b64 s[36:37], -1, 0
	s_and_b64 s[6:7], s[36:37], exec
	v_readlane_b32 s6, v245, 49
	v_mul_f32_e32 v44, v54, v44
	v_cvt_pk_bf16_f32 v44, v44, s0
	ds_write_b16 v3, v44 offset:22672
	v_exp_f32_e64 v44, -v46
	v_mul_f32_e32 v46, 0x3e000000, v139
	v_readlane_b32 s7, v245, 50
	s_cselect_b32 s6, s6, s7
	v_mul_f32_e32 v44, v44, v140
	v_cvt_pk_bf16_f32 v44, v44, s0
	ds_write_b16 v3, v44 offset:41104
	v_mul_f32_e32 v44, v54, v45
	v_cvt_pk_bf16_f32 v44, v44, s0
	ds_write_b16 v3, v44 offset:31888
	v_exp_f32_e64 v44, -v47
	v_exp_f32_e32 v45, v59
	v_readlane_b32 s7, v245, 51
	s_cselect_b32 s7, s7, s8
	v_mul_f32_e32 v44, v44, v140
	v_cvt_pk_bf16_f32 v44, v44, s0
	ds_write_b16 v3, v44 offset:50320
	v_exp_f32_e32 v44, v48
	s_and_b32 s29, s28, 3
	ds_write_b16 v3, v79 offset:22528
	s_lshl_b32 s35, s29, 4
	v_mul_f32_e32 v44, v46, v44
	v_cvt_pk_bf16_f32 v44, v44, s0
	ds_write_b16 v3, v44 offset:22816
	v_exp_f32_e64 v44, -v48
	s_cmp_eq_u32 s29, 0
	s_cselect_b64 s[8:9], -1, 0
	s_cmp_lg_u32 s29, 0
	v_mul_f32_e32 v44, v44, v138
	v_cvt_pk_bf16_f32 v44, v44, s0
	ds_write_b16 v3, v44 offset:41248
	v_mul_f32_e32 v44, v46, v45
	v_cvt_pk_bf16_f32 v44, v44, s0
	ds_write_b16 v3, v44 offset:32032
	v_exp_f32_e64 v44, -v59
	v_mul_f32_e32 v46, 0x3e000000, v137
	v_exp_f32_e32 v45, v58
	v_mov_b32_e32 v47, 0
	v_mul_f32_e32 v44, v44, v138
	v_cvt_pk_bf16_f32 v44, v44, s0
	ds_write_b16 v3, v44 offset:50464
	v_exp_f32_e32 v44, v49
	s_nop 0
	v_mul_f32_e32 v44, v46, v44
	v_cvt_pk_bf16_f32 v44, v44, s0
	ds_write_b16 v3, v44 offset:22960
	v_exp_f32_e64 v44, -v49
	s_nop 0
	v_mul_f32_e32 v44, v44, v136
	v_cvt_pk_bf16_f32 v44, v44, s0
	ds_write_b16 v3, v44 offset:41392
	v_mul_f32_e32 v44, v46, v45
	v_cvt_pk_bf16_f32 v44, v44, s0
	ds_write_b16 v3, v44 offset:32176
	v_exp_f32_e64 v44, -v58
	v_mul_f32_e32 v46, 0x3e000000, v135
	v_exp_f32_e32 v45, v57
	v_mul_f32_e32 v44, v44, v136
	v_cvt_pk_bf16_f32 v44, v44, s0
	ds_write_b16 v3, v44 offset:50608
	v_exp_f32_e32 v44, v50
	s_nop 0
	v_mul_f32_e32 v44, v46, v44
	v_cvt_pk_bf16_f32 v44, v44, s0
	ds_write_b16 v3, v44 offset:23104
	v_exp_f32_e64 v44, -v50
	s_nop 0
	v_mul_f32_e32 v44, v44, v134
	v_cvt_pk_bf16_f32 v44, v44, s0
	ds_write_b16 v3, v44 offset:41536
	v_mul_f32_e32 v44, v46, v45
	v_cvt_pk_bf16_f32 v44, v44, s0
	ds_write_b16 v3, v44 offset:32320
	v_exp_f32_e64 v44, -v57
	v_mul_f32_e32 v46, 0x3e000000, v133
	v_exp_f32_e32 v45, v56
	v_mul_f32_e32 v44, v44, v134
	v_cvt_pk_bf16_f32 v44, v44, s0
	ds_write_b16 v3, v44 offset:50752
	v_exp_f32_e32 v44, v51
	s_nop 0
	v_mul_f32_e32 v44, v46, v44
	v_cvt_pk_bf16_f32 v44, v44, s0
	ds_write_b16 v3, v44 offset:23248
	v_exp_f32_e64 v44, -v51
	s_nop 0
	v_mul_f32_e32 v44, v44, v132
	v_cvt_pk_bf16_f32 v44, v44, s0
	ds_write_b16 v3, v44 offset:41680
	v_mul_f32_e32 v44, v46, v45
	v_cvt_pk_bf16_f32 v44, v44, s0
	ds_write_b16 v3, v44 offset:32464
	v_exp_f32_e64 v44, -v56
	v_mul_f32_e32 v46, 0x3e000000, v131
	v_exp_f32_e32 v45, v55
	v_mul_f32_e32 v44, v44, v132
	v_cvt_pk_bf16_f32 v44, v44, s0
	ds_write_b16 v3, v44 offset:50896
	v_exp_f32_e32 v44, v52
	s_nop 0
	v_mul_f32_e32 v44, v46, v44
	v_cvt_pk_bf16_f32 v44, v44, s0
	ds_write_b16 v3, v44 offset:23392
	v_exp_f32_e64 v44, -v52
	s_nop 0
	v_mul_f32_e32 v44, v44, v130
	v_cvt_pk_bf16_f32 v44, v44, s0
	ds_write_b16 v3, v44 offset:41824
	v_mul_f32_e32 v44, v46, v45
	v_cvt_pk_bf16_f32 v44, v44, s0
	ds_write_b16 v3, v44 offset:32608
	v_exp_f32_e64 v44, -v55
	v_mul_f32_e32 v46, 0x3e000000, v129
	v_exp_f32_e32 v45, v2
	v_exp_f32_e64 v2, -v2
	v_mul_f32_e32 v44, v44, v130
	v_cvt_pk_bf16_f32 v44, v44, s0
	ds_write_b16 v3, v44 offset:51040
	v_exp_f32_e32 v44, v53
	v_mul_f32_e32 v2, v2, v128
	v_cvt_pk_bf16_f32 v2, v2, s0
	ds_write_b16 v3, v2 offset:51184
	v_mul_f32_e32 v44, v46, v44
	v_cvt_pk_bf16_f32 v44, v44, s0
	ds_write_b16 v3, v44 offset:23536
	v_exp_f32_e64 v44, -v53
	v_or_b32_e32 v2, s35, v123
	v_mul_u32_u24_e32 v2, 0x90, v2
	v_mul_f32_e32 v44, v44, v128
	v_cvt_pk_bf16_f32 v44, v44, s0
	ds_write_b16 v3, v44 offset:41968
	v_mul_f32_e32 v44, v46, v45
	v_cvt_pk_bf16_f32 v44, v44, s0
	ds_write_b16 v3, v44 offset:32752
	v_lshrrev_b32_e32 v3, 1, v126
	v_and_b32_e32 v3, 24, v3
	v_lshlrev_b32_e32 v3, 1, v3
	v_add3_u32 v50, s6, v2, v3
	v_add_u32_e32 v2, s7, v3
	s_cselect_b64 s[6:7], -1, 0
	s_or_b64 s[10:11], s[36:37], s[8:9]
	s_andn2_b64 vcc, exec, s[10:11]
	s_movk_i32 s10, 0x90
	v_mov_b32_e32 v44, 0
	v_mad_u32_u24 v51, v123, s10, v2
	v_mov_b32_e32 v45, 0
	v_mov_b32_e32 v46, 0
	s_waitcnt lgkmcnt(0)
	s_barrier
	s_lshr_b32 s9, s28, 2
	s_and_b32 s10, s28, 3
	v_lshrrev_b32_e32 v48, 4, v124
	v_mul_u32_u24_e32 v45, 0x90, v123
	s_mul_i32 s6, s9, 0x2400
	s_mul_i32 s7, s10, 0x900
	v_lshlrev_b32_e32 v2, 2, v48
	v_add_u32_e32 v45, v45, v3
	v_mul_u32_u24_e32 v46, 0x240, v48
	s_add_i32 s8, s6, s7
	v_sub_u32_e32 v47, v123, v2
	v_lshl_add_u32 v46, v123, 1, v46
	s_addk_i32 s8, 0x5800
	v_add_u32_e32 v44, s8, v45
	s_add_i32 s8, s6, 0xa000
	v_add_u32_e32 v45, s8, v45
	s_add_i32 s8, s6, s7
	s_add_i32 s8, s8, 0xe800
	v_add_u32_e32 v46, s8, v46
	ds_read_b128 v[222:225], v44
	ds_read_b128 v[226:229], v44 offset:64
	s_mov_b32 s11, 1
	s_cmp_eq_u32 s9, 0
	s_cbranch_scc1 .Lsc_dir0
	s_mov_b32 s11, -1
	v_sub_u32_e32 v47, 0, v47
.Lsc_dir0:
	s_lshl_b32 s7, s11, 1
	s_mul_i32 s8, s11, 3
	s_sub_i32 s6, s10, 0
	s_mul_i32 s6, s6, s11
	s_cmp_lt_i32 s6, 0
	s_cbranch_scc1 .Lsc_zero0
	ds_read_b128 v[230:233], v45 offset:0
	ds_read_b128 v[234:237], v45 offset:64
	s_waitcnt lgkmcnt(0)
	v_mfma_f32_16x16x32_bf16 v[54:57], v[222:225], v[230:233], 0
	v_mfma_f32_16x16x32_bf16 v[54:57], v[226:229], v[234:237], v[54:57]
	s_cmp_lg_u32 s6, 0
	s_nop 7
	s_nop 1
	s_cbranch_scc1 .Lsc_pack0
	v_cmp_ge_i32_e64 s[38:39], 0, v47
	v_cmp_ge_i32_e64 s[40:41], s11, v47
	v_cmp_ge_i32_e64 s[42:43], s7, v47
	v_cmp_ge_i32_e64 vcc, s8, v47
	s_nop 1
	v_cndmask_b32_e64 v54, 0, v54, s[38:39]
	v_cndmask_b32_e64 v55, 0, v55, s[40:41]
	v_cndmask_b32_e64 v56, 0, v56, s[42:43]
	v_cndmask_b32_e64 v57, 0, v57, vcc
.Lsc_pack0:
	v_cvt_pk_bf16_f32 v58, v54, 0
	v_cvt_pk_bf16_f32 v59, v55, 0
	v_cvt_pk_bf16_f32 v78, v56, 0
	v_cvt_pk_bf16_f32 v79, v57, 0
	ds_write_b16 v46, v58
	ds_write_b16 v46, v59 offset:144
	ds_write_b16 v46, v78 offset:288
	ds_write_b16 v46, v79 offset:432
	s_branch .Lsc_next0
.Lsc_zero0:
	v_mov_b32_e32 v58, 0
	ds_write_b16 v46, v58
	ds_write_b16 v46, v58 offset:144
	ds_write_b16 v46, v58 offset:288
	ds_write_b16 v46, v58 offset:432
.Lsc_next0:
	s_sub_i32 s6, s10, 1
	s_mul_i32 s6, s6, s11
	s_cmp_lt_i32 s6, 0
	s_cbranch_scc1 .Lsc_zero1
	ds_read_b128 v[230:233], v45 offset:2304
	ds_read_b128 v[234:237], v45 offset:2368
	s_waitcnt lgkmcnt(0)
	v_mfma_f32_16x16x32_bf16 v[54:57], v[222:225], v[230:233], 0
	v_mfma_f32_16x16x32_bf16 v[54:57], v[226:229], v[234:237], v[54:57]
	s_cmp_lg_u32 s6, 0
	s_nop 7
	s_nop 1
	s_cbranch_scc1 .Lsc_pack1
	v_cmp_ge_i32_e64 s[38:39], 0, v47
	v_cmp_ge_i32_e64 s[40:41], s11, v47
	v_cmp_ge_i32_e64 s[42:43], s7, v47
	v_cmp_ge_i32_e64 vcc, s8, v47
	s_nop 1
	v_cndmask_b32_e64 v54, 0, v54, s[38:39]
	v_cndmask_b32_e64 v55, 0, v55, s[40:41]
	v_cndmask_b32_e64 v56, 0, v56, s[42:43]
	v_cndmask_b32_e64 v57, 0, v57, vcc
.Lsc_pack1:
	v_cvt_pk_bf16_f32 v58, v54, 0
	v_cvt_pk_bf16_f32 v59, v55, 0
	v_cvt_pk_bf16_f32 v78, v56, 0
	v_cvt_pk_bf16_f32 v79, v57, 0
	ds_write_b16 v46, v58 offset:32
	ds_write_b16 v46, v59 offset:176
	ds_write_b16 v46, v78 offset:320
	ds_write_b16 v46, v79 offset:464
	s_branch .Lsc_next1
.Lsc_zero1:
	v_mov_b32_e32 v58, 0
	ds_write_b16 v46, v58 offset:32
	ds_write_b16 v46, v58 offset:176
	ds_write_b16 v46, v58 offset:320
	ds_write_b16 v46, v58 offset:464
.Lsc_next1:
	s_sub_i32 s6, s10, 2
	s_mul_i32 s6, s6, s11
	s_cmp_lt_i32 s6, 0
	s_cbranch_scc1 .Lsc_zero2
	ds_read_b128 v[230:233], v45 offset:4608
	ds_read_b128 v[234:237], v45 offset:4672
	s_waitcnt lgkmcnt(0)
	v_mfma_f32_16x16x32_bf16 v[54:57], v[222:225], v[230:233], 0
	v_mfma_f32_16x16x32_bf16 v[54:57], v[226:229], v[234:237], v[54:57]
	s_cmp_lg_u32 s6, 0
	s_nop 7
	s_nop 1
	s_cbranch_scc1 .Lsc_pack2
	v_cmp_ge_i32_e64 s[38:39], 0, v47
	v_cmp_ge_i32_e64 s[40:41], s11, v47
	v_cmp_ge_i32_e64 s[42:43], s7, v47
	v_cmp_ge_i32_e64 vcc, s8, v47
	s_nop 1
	v_cndmask_b32_e64 v54, 0, v54, s[38:39]
	v_cndmask_b32_e64 v55, 0, v55, s[40:41]
	v_cndmask_b32_e64 v56, 0, v56, s[42:43]
	v_cndmask_b32_e64 v57, 0, v57, vcc
.Lsc_pack2:
	v_cvt_pk_bf16_f32 v58, v54, 0
	v_cvt_pk_bf16_f32 v59, v55, 0
	v_cvt_pk_bf16_f32 v78, v56, 0
	v_cvt_pk_bf16_f32 v79, v57, 0
	ds_write_b16 v46, v58 offset:64
	ds_write_b16 v46, v59 offset:208
	ds_write_b16 v46, v78 offset:352
	ds_write_b16 v46, v79 offset:496
	s_branch .Lsc_next2
.Lsc_zero2:
	v_mov_b32_e32 v58, 0
	ds_write_b16 v46, v58 offset:64
	ds_write_b16 v46, v58 offset:208
	ds_write_b16 v46, v58 offset:352
	ds_write_b16 v46, v58 offset:496
.Lsc_next2:
	s_sub_i32 s6, s10, 3
	s_mul_i32 s6, s6, s11
	s_cmp_lt_i32 s6, 0
	s_cbranch_scc1 .Lsc_zero3
	ds_read_b128 v[230:233], v45 offset:6912
	ds_read_b128 v[234:237], v45 offset:6976
	s_waitcnt lgkmcnt(0)
	v_mfma_f32_16x16x32_bf16 v[54:57], v[222:225], v[230:233], 0
	v_mfma_f32_16x16x32_bf16 v[54:57], v[226:229], v[234:237], v[54:57]
	s_cmp_lg_u32 s6, 0
	s_nop 7
	s_nop 1
	s_cbranch_scc1 .Lsc_pack3
	v_cmp_ge_i32_e64 s[38:39], 0, v47
	v_cmp_ge_i32_e64 s[40:41], s11, v47
	v_cmp_ge_i32_e64 s[42:43], s7, v47
	v_cmp_ge_i32_e64 vcc, s8, v47
	s_nop 1
	v_cndmask_b32_e64 v54, 0, v54, s[38:39]
	v_cndmask_b32_e64 v55, 0, v55, s[40:41]
	v_cndmask_b32_e64 v56, 0, v56, s[42:43]
	v_cndmask_b32_e64 v57, 0, v57, vcc
.Lsc_pack3:
	v_cvt_pk_bf16_f32 v58, v54, 0
	v_cvt_pk_bf16_f32 v59, v55, 0
	v_cvt_pk_bf16_f32 v78, v56, 0
	v_cvt_pk_bf16_f32 v79, v57, 0
	ds_write_b16 v46, v58 offset:96
	ds_write_b16 v46, v59 offset:240
	ds_write_b16 v46, v78 offset:384
	ds_write_b16 v46, v79 offset:528
	s_branch .Lsc_next3
.Lsc_zero3:
	v_mov_b32_e32 v58, 0
	ds_write_b16 v46, v58 offset:96
	ds_write_b16 v46, v58 offset:240
	ds_write_b16 v46, v58 offset:384
	ds_write_b16 v46, v58 offset:528
.Lsc_next3:
	s_lshl_b32 s8, s28, 4
	v_or_b32_e32 v44, s8, v123
	s_movk_i32 s7, 0x90
	v_mul_lo_u32 v44, v44, s7
	v_add_u32_e32 v86, 0, v3
	v_add3_u32 v44, s92, v44, v3
	v_lshlrev_b32_e32 v52, 4, v48
	v_mad_u32_u24 v48, v123, s7, v86
	s_waitcnt lgkmcnt(0)
	s_barrier
	s_add_i32 s6, 0, 0x10c00
	v_cmp_gt_u32_e32 vcc, 16, v124
	ds_read_b128 v[78:81], v44
	ds_read_b128 v[56:59], v44 offset:64
	v_add_u32_e32 v173, s6, v3
	v_mad_u32_u24 v180, v123, s7, v217
	v_mad_u32_u24 v181, v123, s7, v218
	v_mad_u32_u24 v182, v123, s7, v219
	v_mul_u32_u24_e32 v243, 0x48, v123
	v_add_u32_e32 v174, v173, v180
	v_add_u32_e32 v175, v173, v181
	v_add_u32_e32 v242, v173, v182
	v_mad_u32_u24 v173, v123, s7, v173
	v_lshlrev_b32_e32 v243, 1, v243
	v_add_u32_e32 v180, v86, v180
	v_add_u32_e32 v181, v86, v181
	v_add_u32_e32 v182, v86, v182
	v_add3_u32 v243, 0, v52, v243
	ds_read_b128 v[222:225], v48 offset:59392
	ds_read_b128 v[226:229], v48 offset:59456
	ds_read_b128 v[230:233], v173
	ds_read_b128 v[234:237], v173 offset:64
	ds_read_b128 v[238:241], v243 offset:22528
	ds_read_b128 v[196:199], v243 offset:22592
	ds_read_b128 v[200:203], v243 offset:31744
	ds_read_b128 v[176:179], v243 offset:31808
	s_waitcnt lgkmcnt(7)
	v_mfma_f32_16x16x32_bf16 v[52:55], v[78:81], v[222:225], 0
	s_waitcnt lgkmcnt(6)
	v_mfma_f32_16x16x32_bf16 v[52:55], v[56:59], v[226:229], v[52:55]
	s_waitcnt lgkmcnt(5)
	v_mfma_f32_16x16x32_bf16 v[52:55], v[78:81], v[230:233], v[52:55]
	s_waitcnt lgkmcnt(4)
	v_mfma_f32_16x16x32_bf16 v[52:55], v[56:59], v[234:237], v[52:55]
	s_waitcnt lgkmcnt(3)
	v_mfma_f32_16x16x32_bf16 v[52:55], v[8:11], v[238:241], v[52:55]
	s_waitcnt lgkmcnt(2)
	v_mfma_f32_16x16x32_bf16 v[52:55], v[12:15], v[196:199], v[52:55]
	s_waitcnt lgkmcnt(1)
	v_mfma_f32_16x16x32_bf16 v[52:55], v[16:19], v[200:203], v[52:55]
	s_waitcnt lgkmcnt(0)
	v_mfma_f32_16x16x32_bf16 v[52:55], v[20:23], v[176:179], v[52:55]
	ds_read_b128 v[222:225], v180 offset:59392
	ds_read_b128 v[226:229], v180 offset:59456
	ds_read_b128 v[230:233], v174
	ds_read_b128 v[234:237], v174 offset:64
	ds_read_b128 v[238:241], v243 offset:24832
	ds_read_b128 v[196:199], v243 offset:24896
	ds_read_b128 v[200:203], v243 offset:34048
	ds_read_b128 v[176:179], v243 offset:34112
	s_waitcnt lgkmcnt(7)
	v_mfma_f32_16x16x32_bf16 v[48:51], v[78:81], v[222:225], 0
	s_waitcnt lgkmcnt(6)
	v_mfma_f32_16x16x32_bf16 v[48:51], v[56:59], v[226:229], v[48:51]
	s_waitcnt lgkmcnt(5)
	v_mfma_f32_16x16x32_bf16 v[48:51], v[78:81], v[230:233], v[48:51]
	s_waitcnt lgkmcnt(4)
	v_mfma_f32_16x16x32_bf16 v[48:51], v[56:59], v[234:237], v[48:51]
	s_waitcnt lgkmcnt(3)
	v_mfma_f32_16x16x32_bf16 v[48:51], v[8:11], v[238:241], v[48:51]
	s_waitcnt lgkmcnt(2)
	v_mfma_f32_16x16x32_bf16 v[48:51], v[12:15], v[196:199], v[48:51]
	s_waitcnt lgkmcnt(1)
	v_mfma_f32_16x16x32_bf16 v[48:51], v[16:19], v[200:203], v[48:51]
	s_waitcnt lgkmcnt(0)
	v_mfma_f32_16x16x32_bf16 v[48:51], v[20:23], v[176:179], v[48:51]
	ds_read_b128 v[222:225], v181 offset:59392
	ds_read_b128 v[226:229], v181 offset:59456
	ds_read_b128 v[230:233], v175
	ds_read_b128 v[234:237], v175 offset:64
	ds_read_b128 v[238:241], v243 offset:27136
	ds_read_b128 v[196:199], v243 offset:27200
	ds_read_b128 v[200:203], v243 offset:36352
	ds_read_b128 v[176:179], v243 offset:36416
	s_waitcnt lgkmcnt(7)
	v_mfma_f32_16x16x32_bf16 v[44:47], v[78:81], v[222:225], 0
	s_waitcnt lgkmcnt(6)
	v_mfma_f32_16x16x32_bf16 v[44:47], v[56:59], v[226:229], v[44:47]
	s_waitcnt lgkmcnt(5)
	v_mfma_f32_16x16x32_bf16 v[44:47], v[78:81], v[230:233], v[44:47]
	s_waitcnt lgkmcnt(4)
	v_mfma_f32_16x16x32_bf16 v[44:47], v[56:59], v[234:237], v[44:47]
	s_waitcnt lgkmcnt(3)
	v_mfma_f32_16x16x32_bf16 v[44:47], v[8:11], v[238:241], v[44:47]
	s_waitcnt lgkmcnt(2)
	v_mfma_f32_16x16x32_bf16 v[44:47], v[12:15], v[196:199], v[44:47]
	s_waitcnt lgkmcnt(1)
	v_mfma_f32_16x16x32_bf16 v[44:47], v[16:19], v[200:203], v[44:47]
	s_waitcnt lgkmcnt(0)
	v_mfma_f32_16x16x32_bf16 v[44:47], v[20:23], v[176:179], v[44:47]
	ds_read_b128 v[222:225], v182 offset:59392
	ds_read_b128 v[226:229], v182 offset:59456
	ds_read_b128 v[230:233], v242
	ds_read_b128 v[234:237], v242 offset:64
	ds_read_b128 v[238:241], v243 offset:29440
	ds_read_b128 v[196:199], v243 offset:29504
	ds_read_b128 v[200:203], v243 offset:38656
	ds_read_b128 v[176:179], v243 offset:38720
	v_mul_f32_e32 v3, v53, v53
	v_fmac_f32_e32 v3, v52, v52
	v_fmac_f32_e32 v3, v54, v54
	v_fmac_f32_e32 v3, v55, v55
	s_waitcnt lgkmcnt(7)
	v_mfma_f32_16x16x32_bf16 v[82:85], v[78:81], v[222:225], 0
	s_waitcnt lgkmcnt(6)
	v_mfma_f32_16x16x32_bf16 v[82:85], v[56:59], v[226:229], v[82:85]
	s_waitcnt lgkmcnt(5)
	v_mfma_f32_16x16x32_bf16 v[82:85], v[78:81], v[230:233], v[82:85]
	s_waitcnt lgkmcnt(4)
	v_mfma_f32_16x16x32_bf16 v[82:85], v[56:59], v[234:237], v[82:85]
	s_waitcnt lgkmcnt(3)
	v_mfma_f32_16x16x32_bf16 v[8:11], v[8:11], v[238:241], v[82:85]
	s_waitcnt lgkmcnt(2)
	v_mfma_f32_16x16x32_bf16 v[8:11], v[12:15], v[196:199], v[8:11]
	s_waitcnt lgkmcnt(1)
	v_mfma_f32_16x16x32_bf16 v[8:11], v[16:19], v[200:203], v[8:11]
	s_waitcnt lgkmcnt(0)
	v_mfma_f32_16x16x32_bf16 v[8:11], v[20:23], v[176:179], v[8:11]
	v_mul_f32_e32 v13, v49, v49
	v_mul_f32_e32 v15, v45, v45
	v_fmac_f32_e32 v13, v48, v48
	s_nop 4
	v_mul_f32_e32 v17, v9, v9
	v_fmac_f32_e32 v15, v44, v44
	v_fmac_f32_e32 v17, v8, v8
	v_fmac_f32_e32 v13, v50, v50
	v_fmac_f32_e32 v15, v46, v46
	v_fmac_f32_e32 v17, v10, v10
	v_fmac_f32_e32 v13, v51, v51
	v_fmac_f32_e32 v15, v47, v47
	v_fmac_f32_e32 v17, v11, v11
	ds_bpermute_b32 v12, v209, v3
	ds_bpermute_b32 v14, v209, v13
	ds_bpermute_b32 v16, v209, v15
	ds_bpermute_b32 v18, v209, v17
	s_waitcnt lgkmcnt(0)
	v_add_f32_e32 v3, v3, v12
	v_add_f32_e32 v13, v13, v14
	v_add_f32_e32 v15, v15, v16
	v_add_f32_e32 v17, v17, v18
	ds_bpermute_b32 v12, v215, v3
	ds_bpermute_b32 v14, v215, v13
	ds_bpermute_b32 v16, v215, v15
	ds_bpermute_b32 v18, v215, v17
	s_and_saveexec_b64 s[6:7], vcc
	s_cbranch_execz .LBB0_177
	s_and_b32 s9, s27, 0x3fffffc0
	s_lshl_b32 s9, s9, 2
	s_add_i32 s9, s9, 0
	s_waitcnt lgkmcnt(0)
	v_add_f32_e32 v3, v3, v12
	v_lshl_add_u32 v12, v123, 2, s9
	v_add_f32_e32 v13, v13, v14
	v_add_u32_e32 v12, 0x5000, v12
	v_add_f32_e32 v17, v17, v18
	v_add_f32_e32 v15, v15, v16
	ds_write2_b32 v12, v3, v13 offset1:16
	ds_write2_b32 v12, v15, v17 offset0:32 offset1:48
	s_branch .LBB0_177
